# MLA latent loop: dead alpha<1 re-test on the no-rescale path (alpha was just set to 1.0) replaced by an unconditional branch (asm guide 7.12)
# speedup vs baseline: 1.0029x; 1.0012x over previous
.LBB0_511:
	v_max_f32_e32 v144, v81, v81
	v_max_f32_e32 v145, v80, v80
	v_max_f32_e32 v144, v145, v144
	v_max3_f32 v144, v144, v82, v83
	v_max3_f32 v144, v144, v84, v85
	v_max3_f32 v144, v144, v86, v87
	v_max3_f32 v144, v144, v88, v89
	v_max3_f32 v144, v144, v90, v91
	v_max3_f32 v144, v144, v92, v93
	v_max3_f32 v144, v144, v94, v95
	v_max3_f32 v144, v144, v64, v65
	v_max3_f32 v144, v144, v66, v67
	v_max3_f32 v144, v144, v68, v69
	v_max3_f32 v144, v144, v70, v71
	v_max3_f32 v144, v144, v72, v73
	v_max3_f32 v144, v144, v74, v75
	v_max3_f32 v144, v144, v76, v77
	v_max3_f32 v144, v144, v78, v79
	v_mov_b32_e32 v145, v144
	s_nop 1
	v_permlane32_swap_b32_e32 v144, v145
	v_max_f32_e32 v145, v145, v145
	v_max_f32_e32 v144, v144, v144
	v_max_f32_e32 v144, v144, v145
	v_cmp_ge_f32_e32 vcc, s39, v144
	s_mov_b32 s45, s47
	s_cmp_eq_u64 vcc, exec
	v_mov_b32_e32 v168, 1.0
	s_cbranch_scc0 .LBB0_518
	s_branch .LBB0_514
